# attention inner loop hand-rescheduled: softmax VALU interleaved into MFMA shadows, K/V global loads one iteration ahead
# speedup vs baseline: 1.0316x; 1.0316x over previous
.LBB0_1338:
	v_mov_b32_e32 v54, v191
	s_lshl_b32 s97, s4, 8
	s_add_i32 s97, s97, s79
	v_and_b32_e32 v48, 31, v54
	v_or_b32_e32 v0, s97, v48
	v_ashrrev_i32_e32 v50, 3, v54
	v_and_b32_e32 v56, 7, v54
	v_bfe_u32 v49, v54, 5, 1
	v_add_u32_e32 v0, s91, v0
	s_movk_i32 s0, 0xc00
	v_ashrrev_i32_e32 v51, 4, v54
	v_and_b32_e32 v55, 15, v54
	v_add_u32_e32 v9, s91, v50
	v_lshlrev_b32_e32 v52, 3, v56
	v_ashrrev_i32_e32 v1, 31, v0
	v_mad_i64_i32 v[2:3], s[0:1], v0, s0, v[182:183]
	v_lshlrev_b32_e32 v180, 4, v49
	v_add_lshl_u32 v8, v51, s91, 10
	v_lshlrev_b32_e32 v53, 3, v55
	v_lshl_or_b32 v10, v9, 6, v52
	v_add_lshl_u32 v9, v50, s92, 15
	v_lshl_add_u64 v[24:25], v[2:3], 0, v[180:181]
	v_lshlrev_b64 v[0:1], 7, v[0:1]
	v_or3_b32 v8, v8, v53, s92
	v_or3_b32 v12, v9, s91, v52
	v_mov_b32_e32 v9, v181
	global_load_dwordx4 v[96:99], v[24:25], off
	global_load_dwordx4 v[100:103], v[24:25], off offset:32
	global_load_dwordx4 v[104:107], v[24:25], off offset:64
	global_load_dwordx4 v[108:111], v[24:25], off offset:96
	global_load_dwordx4 v[112:115], v[24:25], off offset:128
	global_load_dwordx4 v[116:119], v[24:25], off offset:160
	global_load_dwordx4 v[120:123], v[24:25], off offset:192
	global_load_dwordx4 v[124:127], v[24:25], off offset:224
	v_lshl_add_u64 v[2:3], s[62:63], 0, v[0:1]
	v_lshlrev_b32_e32 v4, 5, v49
	v_mov_b32_e32 v5, v181
	v_lshl_add_u64 v[14:15], v[8:9], 1, s[64:65]
	v_add_u32_e32 v8, 0x8000, v8
	v_lshl_add_u64 v[28:29], v[2:3], 0, v[4:5]
	v_lshl_add_u64 v[0:1], s[66:67], 0, v[0:1]
	v_lshl_add_u64 v[8:9], v[8:9], 1, s[64:65]
	v_mov_b32_e32 v11, v181
	v_lshl_add_u64 v[44:45], v[0:1], 0, v[4:5]
	global_load_dwordx4 v[0:3], v[28:29], off offset:16
	global_load_dwordx4 v[4:7], v[28:29], off
	global_load_dwordx4 v[128:131], v[14:15], off
	global_load_dwordx4 v[132:135], v[8:9], off
	v_lshl_add_u64 v[8:9], v[10:11], 1, s[60:61]
	v_mov_b32_e32 v13, v181
	v_lshl_add_u64 v[10:11], v[12:13], 1, s[68:69]
	global_load_dwordx4 v[136:139], v[8:9], off
	global_load_dwordx4 v[140:143], v[10:11], off
	v_add_u32_e32 v8, 0x200000, v12
	v_mov_b32_e32 v9, v181
	v_lshl_add_u64 v[8:9], v[8:9], 1, s[68:69]
	global_load_dwordx4 v[144:147], v[8:9], off
	s_nop 0
	global_load_dwordx4 v[8:11], v[44:45], off offset:16
	global_load_dwordx4 v[20:23], v[44:45], off
	global_load_dwordx4 v[12:15], v[24:25], off offset:256
	global_load_dwordx4 v[32:35], v[24:25], off offset:288
	global_load_dwordx4 v[16:19], v[24:25], off offset:320
	global_load_dwordx4 v[36:39], v[24:25], off offset:352
	s_nop 0
	global_load_dwordx4 v[24:27], v[28:29], off offset:80
	global_load_dwordx4 v[40:43], v[28:29], off offset:64
	s_nop 0
	global_load_dwordx4 v[28:31], v[44:45], off offset:80
	s_nop 0
	global_load_dwordx4 v[44:47], v[44:45], off offset:64
	v_lshlrev_b32_e32 v57, 3, v54
	v_mul_lo_u32 v58, v51, s82
	v_lshlrev_b32_e32 v54, 4, v56
	v_mul_lo_u32 v56, v50, s83
	v_lshl_add_u32 v194, v55, 4, v58
	v_and_b32_e32 v55, 0x60, v54
	v_and_b32_e32 v57, 8, v57
	v_mad_u64_u32 v[184:185], s[0:1], v50, s82, v[54:55]
	v_add_u32_e32 v54, 0, v56
	v_add3_u32 v185, v54, v57, v55
	v_add_u32_e32 v56, 0, v194
	v_add_u32_e32 v54, 0xc800, v185
	v_add_u32_e32 v58, 0, v184
	v_add_u32_e32 v55, 0xe800, v185
	s_cmp_lt_i32 s4, 0
	s_mov_b32 s52, 0
	s_waitcnt vmcnt(0)
	ds_write_b128 v56, v[128:131]
	ds_write_b128 v56, v[132:135] offset:12800
	ds_write_b128 v58, v[136:139] offset:256
	ds_write2_b64 v54, v[140:141], v[142:143] offset1:2
	ds_write2_b64 v55, v[144:145], v[146:147] offset0:128 offset1:130
	v_mad_u32_u24 v54, v48, s83, 0
	v_add_u32_e32 v195, v54, v180
	v_add_u32_e32 v173, 0xc800, v195
	s_waitcnt lgkmcnt(0)
	s_barrier
	s_cbranch_scc1 .LBB0_1331
	v_lshlrev_b32_e32 v55, 8, v48
	v_add3_u32 v196, v54, v55, v180
	v_and_b32_e32 v55, 0xffff0000, v36
	v_lshlrev_b32_e32 v54, 16, v36
	v_and_b32_e32 v57, 0xffff0000, v32
	v_lshlrev_b32_e32 v56, 16, v32
	v_pk_mul_f32 v[58:59], v[44:45], v[56:57]
	v_pk_mul_f32 v[44:45], v[44:45], v[54:55]
	v_pk_fma_f32 v[58:59], v[40:41], v[54:55], v[58:59]
	v_pk_fma_f32 v[40:41], v[40:41], v[56:57], v[44:45] neg_lo:[0,0,1] neg_hi:[0,0,1]
	v_lshlrev_b32_e32 v36, 16, v33
	v_cvt_pk_bf16_f32 v152, v40, v41
	v_and_b32_e32 v41, 0xffff0000, v37
	v_lshlrev_b32_e32 v40, 16, v37
	v_and_b32_e32 v37, 0xffff0000, v33
	v_pk_mul_f32 v[32:33], v[46:47], v[36:37]
	s_lshl_b32 s53, s4, 2
	v_pk_fma_f32 v[32:33], v[42:43], v[40:41], v[32:33]
	v_mov_b32_e32 v200, 0
	v_cvt_pk_bf16_f32 v149, v32, v33
	v_pk_mul_f32 v[32:33], v[46:47], v[40:41]
	s_add_i32 s53, s53, 4
	v_pk_fma_f32 v[32:33], v[42:43], v[36:37], v[32:33] neg_lo:[0,0,1] neg_hi:[0,0,1]
	v_and_b32_e32 v37, 0xffff0000, v34
	v_cvt_pk_bf16_f32 v153, v32, v33
	v_and_b32_e32 v33, 0xffff0000, v38
	v_lshlrev_b32_e32 v32, 16, v38
	v_lshlrev_b32_e32 v36, 16, v34
	v_pk_mul_f32 v[40:41], v[28:29], v[36:37]
	v_pk_mul_f32 v[28:29], v[28:29], v[32:33]
	v_pk_fma_f32 v[40:41], v[24:25], v[32:33], v[40:41]
	v_pk_fma_f32 v[24:25], v[24:25], v[36:37], v[28:29] neg_lo:[0,0,1] neg_hi:[0,0,1]
	v_and_b32_e32 v29, 0xffff0000, v35
	v_lshlrev_b32_e32 v28, 16, v35
	v_cvt_pk_bf16_f32 v154, v24, v25
	v_and_b32_e32 v25, 0xffff0000, v39
	v_lshlrev_b32_e32 v24, 16, v39
	v_pk_mul_f32 v[32:33], v[30:31], v[28:29]
	v_cvt_pk_bf16_f32 v148, v58, v59
	v_pk_fma_f32 v[32:33], v[26:27], v[24:25], v[32:33]
	v_pk_mul_f32 v[24:25], v[30:31], v[24:25]
	v_cvt_pk_bf16_f32 v150, v40, v41
	v_pk_fma_f32 v[24:25], v[26:27], v[28:29], v[24:25] neg_lo:[0,0,1] neg_hi:[0,0,1]
	v_and_b32_e32 v27, 0xffff0000, v12
	v_cvt_pk_bf16_f32 v155, v24, v25
	v_and_b32_e32 v25, 0xffff0000, v16
	v_lshlrev_b32_e32 v24, 16, v16
	v_lshlrev_b32_e32 v26, 16, v12
	v_pk_mul_f32 v[28:29], v[20:21], v[26:27]
	v_pk_mul_f32 v[20:21], v[20:21], v[24:25]
	v_pk_fma_f32 v[28:29], v[4:5], v[24:25], v[28:29]
	v_pk_fma_f32 v[4:5], v[4:5], v[26:27], v[20:21] neg_lo:[0,0,1] neg_hi:[0,0,1]
	v_lshlrev_b32_e32 v16, 16, v13
	v_cvt_pk_bf16_f32 v160, v4, v5
	v_and_b32_e32 v5, 0xffff0000, v17
	v_lshlrev_b32_e32 v4, 16, v17
	v_and_b32_e32 v17, 0xffff0000, v13
	v_pk_mul_f32 v[12:13], v[22:23], v[16:17]
	v_cvt_pk_bf16_f32 v151, v32, v33
	v_pk_fma_f32 v[12:13], v[6:7], v[4:5], v[12:13]
	v_pk_mul_f32 v[4:5], v[22:23], v[4:5]
	v_cvt_pk_bf16_f32 v157, v12, v13
	v_pk_fma_f32 v[4:5], v[6:7], v[16:17], v[4:5] neg_lo:[0,0,1] neg_hi:[0,0,1]
	v_and_b32_e32 v7, 0xffff0000, v14
	v_lshlrev_b32_e32 v6, 16, v14
	v_cvt_pk_bf16_f32 v161, v4, v5
	v_and_b32_e32 v5, 0xffff0000, v18
	v_lshlrev_b32_e32 v4, 16, v18
	v_pk_mul_f32 v[12:13], v[8:9], v[6:7]
	v_cvt_pk_bf16_f32 v156, v28, v29
	v_pk_fma_f32 v[12:13], v[0:1], v[4:5], v[12:13]
	v_pk_mul_f32 v[4:5], v[8:9], v[4:5]
	v_cvt_pk_bf16_f32 v158, v12, v13
	v_pk_fma_f32 v[0:1], v[0:1], v[6:7], v[4:5] neg_lo:[0,0,1] neg_hi:[0,0,1]
	v_and_b32_e32 v5, 0xffff0000, v15
	v_lshlrev_b32_e32 v4, 16, v15
	v_cvt_pk_bf16_f32 v162, v0, v1
	v_and_b32_e32 v1, 0xffff0000, v19
	v_lshlrev_b32_e32 v0, 16, v19
	v_pk_mul_f32 v[6:7], v[10:11], v[4:5]
	v_mov_b32_e32 v199, 0xf149f2ca
	v_pk_fma_f32 v[6:7], v[2:3], v[0:1], v[6:7]
	v_pk_mul_f32 v[0:1], v[10:11], v[0:1]
	v_cvt_pk_bf16_f32 v159, v6, v7
	v_pk_fma_f32 v[0:1], v[2:3], v[4:5], v[0:1] neg_lo:[0,0,1] neg_hi:[0,0,1]
	s_mov_b32 s33, 63
	v_cvt_pk_bf16_f32 v163, v0, v1
	v_lshlrev_b32_e32 v1, 10, v51
	v_lshlrev_b32_e32 v0, 2, v49
	v_add3_u32 v186, s93, v1, v53
	v_add_u32_e32 v1, s97, v48
	v_sub_u32_e32 v197, v1, v0
	v_lshlrev_b32_e32 v0, 6, v50
	v_add3_u32 v188, s94, v0, v52
	v_lshlrev_b32_e32 v0, 15, v50
	v_add3_u32 v198, s95, v0, v52
	v_mov_b32_e32 v64, 0
	v_mov_b32_e32 v65, 0
	v_mov_b32_e32 v66, 0
	v_mov_b32_e32 v67, 0
	v_mov_b32_e32 v68, 0
	v_mov_b32_e32 v69, 0
	v_mov_b32_e32 v70, 0
	v_mov_b32_e32 v71, 0
	s_mov_b32 s0, 0
	v_mov_b32_e32 v0, 0
	v_mov_b32_e32 v1, v200
	v_mov_b32_e32 v2, v200
	v_mov_b32_e32 v3, v200
	v_mov_b32_e32 v4, v200
	v_mov_b32_e32 v5, v200
	v_mov_b32_e32 v6, v200
	v_mov_b32_e32 v7, v200
	v_mov_b32_e32 v8, v200
	v_mov_b32_e32 v9, v200
	v_mov_b32_e32 v10, v200
	v_mov_b32_e32 v11, v200
	v_mov_b32_e32 v12, v200
	v_mov_b32_e32 v13, v200
	v_mov_b32_e32 v14, v200
	v_mov_b32_e32 v15, v200
	v_mov_b32_e32 v16, 0
	v_mov_b32_e32 v17, v200
	v_mov_b32_e32 v18, v200
	v_mov_b32_e32 v19, v200
	v_mov_b32_e32 v20, v200
	v_mov_b32_e32 v21, v200
	v_mov_b32_e32 v22, v200
	v_mov_b32_e32 v23, v200
	v_mov_b32_e32 v24, v200
	v_mov_b32_e32 v25, v200
	v_mov_b32_e32 v26, v200
	v_mov_b32_e32 v27, v200
	v_mov_b32_e32 v28, v200
	v_mov_b32_e32 v29, v200
	v_mov_b32_e32 v30, v200
	v_mov_b32_e32 v31, v200
	v_mov_b32_e32 v32, 0
	v_mov_b32_e32 v33, v200
	v_mov_b32_e32 v34, v200
	v_mov_b32_e32 v35, v200
	v_mov_b32_e32 v36, v200
	v_mov_b32_e32 v37, v200
	v_mov_b32_e32 v38, v200
	v_mov_b32_e32 v39, v200
	v_mov_b32_e32 v40, v200
	v_mov_b32_e32 v41, v200
	v_mov_b32_e32 v42, v200
	v_mov_b32_e32 v43, v200
	v_mov_b32_e32 v44, v200
	v_mov_b32_e32 v45, v200
	v_mov_b32_e32 v46, v200
	v_mov_b32_e32 v47, v200
	v_mov_b32_e32 v48, 0
	v_mov_b32_e32 v49, v200
	v_mov_b32_e32 v50, v200
	v_mov_b32_e32 v51, v200
	v_mov_b32_e32 v52, v200
	v_mov_b32_e32 v53, v200
	v_mov_b32_e32 v54, v200
	v_mov_b32_e32 v55, v200
	v_mov_b32_e32 v56, v200
	v_mov_b32_e32 v57, v200
	v_mov_b32_e32 v58, v200
	v_mov_b32_e32 v59, v200
	v_mov_b32_e32 v60, v200
	v_mov_b32_e32 v61, v200
	v_mov_b32_e32 v62, v200
	v_mov_b32_e32 v63, v200
	v_mov_b32_e32 v187, 0
	v_mov_b32_e32 v189, 0
	v_xor_b32_e32 v246, 32, v193
	v_lshlrev_b32_e32 v246, 2, v246
	v_mov_b32_e32 v64, 0xff61b1e6
	v_mov_b32_e32 v65, v64
	v_mov_b32_e32 v66, v64
	v_mov_b32_e32 v67, v64
	v_mov_b32_e32 v68, v64
	v_mov_b32_e32 v69, v64
	v_mov_b32_e32 v70, v64
	v_mov_b32_e32 v71, v64
	v_mov_b32_e32 v72, v64
	v_mov_b32_e32 v73, v64
	v_mov_b32_e32 v74, v64
	v_mov_b32_e32 v75, v64
	v_mov_b32_e32 v76, v64
	v_mov_b32_e32 v77, v64
	v_mov_b32_e32 v78, v64
	v_mov_b32_e32 v79, v64
	v_add_u32_e32 v180, 0xffff8000, v186
	v_lshl_add_u64 v[244:245], v[180:181], 1, s[64:65]
	global_load_dwordx4 v[128:131], v[244:245], off
	v_lshl_add_u64 v[244:245], v[186:187], 1, s[64:65]
	global_load_dwordx4 v[132:135], v[244:245], off
	v_lshl_add_u64 v[244:245], v[188:189], 1, s[60:61]
	global_load_dwordx4 v[136:139], v[244:245], off
	v_add_u32_e32 v235, s33, v198
	v_add_u32_e32 v180, 1, v235
	v_lshl_add_u64 v[244:245], v[180:181], 1, s[68:69]
	global_load_dwordx4 v[140:143], v[244:245], off
	v_add_u32_e32 v180, 0x200001, v235
	v_lshl_add_u64 v[244:245], v[180:181], 1, s[68:69]
	global_load_dwordx4 v[144:147], v[244:245], off
.LBB0_1340:
	s_add_i32 s54, s0, 1
	s_bitcmp1_b32 s0, 0
	s_cselect_b32 s4, 0x6400, 0
	v_add_u32_e32 v174, s4, v196
	s_mul_i32 s4, s52, 0x4800
	v_add_u32_e32 v234, s4, v195
	ds_read_b128 v[202:205], v174 offset:0
	ds_read_b128 v[206:209], v174 offset:32
	ds_read_b128 v[210:213], v174 offset:64
	ds_read_b128 v[214:217], v174 offset:96
	ds_read_b128 v[218:221], v174 offset:128
	ds_read_b128 v[222:225], v174 offset:160
	v_fma_f32 v64, v64, s84, -v199
	v_exp_f32_e32 v64, v64
	v_fma_f32 v65, v65, s84, -v199
	v_exp_f32_e32 v65, v65
	v_add_f32_e32 v200, v200, v64
	v_fma_f32 v66, v66, s84, -v199
	v_exp_f32_e32 v66, v66
	v_add_f32_e32 v200, v200, v65
	s_waitcnt lgkmcnt(5)
	v_mfma_f32_32x32x16_bf16 v[80:95], v[202:205], v[96:99], 0
	ds_read_b128 v[202:205], v174 offset:192
	v_fma_f32 v67, v67, s84, -v199
	v_exp_f32_e32 v67, v67
	v_add_f32_e32 v200, v200, v66
	v_fma_f32 v68, v68, s84, -v199
	s_waitcnt lgkmcnt(5)
	v_mfma_f32_32x32x16_bf16 v[80:95], v[206:209], v[100:103], v[80:95]
	ds_read_b128 v[206:209], v174 offset:224
	v_exp_f32_e32 v68, v68
	v_add_f32_e32 v200, v200, v67
	v_fma_f32 v69, v69, s84, -v199
	v_exp_f32_e32 v69, v69
	s_waitcnt lgkmcnt(5)
	v_mfma_f32_32x32x16_bf16 v[80:95], v[210:213], v[104:107], v[80:95]
	ds_read_b128 v[210:213], v174 offset:256
	v_add_f32_e32 v200, v200, v68
	v_fma_f32 v70, v70, s84, -v199
	v_exp_f32_e32 v70, v70
	v_add_f32_e32 v200, v200, v69
	s_waitcnt lgkmcnt(5)
	v_mfma_f32_32x32x16_bf16 v[80:95], v[214:217], v[108:111], v[80:95]
	ds_read_b128 v[214:217], v174 offset:288
	v_fma_f32 v71, v71, s84, -v199
	v_exp_f32_e32 v71, v71
	v_add_f32_e32 v200, v200, v70
	v_fma_f32 v72, v72, s84, -v199
	s_waitcnt lgkmcnt(5)
	v_mfma_f32_32x32x16_bf16 v[80:95], v[218:221], v[112:115], v[80:95]
	ds_read_b128 v[218:221], v174 offset:320
	v_exp_f32_e32 v72, v72
	v_add_f32_e32 v200, v200, v71
	v_fma_f32 v73, v73, s84, -v199
	v_exp_f32_e32 v73, v73
	s_waitcnt lgkmcnt(5)
	v_mfma_f32_32x32x16_bf16 v[80:95], v[222:225], v[116:119], v[80:95]
	ds_read_b128 v[222:225], v174 offset:352
	v_add_f32_e32 v200, v200, v72
	v_fma_f32 v74, v74, s84, -v199
	v_exp_f32_e32 v74, v74
	v_add_f32_e32 v200, v200, v73
	s_waitcnt lgkmcnt(5)
	v_mfma_f32_32x32x16_bf16 v[80:95], v[202:205], v[120:123], v[80:95]
	ds_read_b128 v[164:167], v173 offset:0
	v_fma_f32 v75, v75, s84, -v199
	v_exp_f32_e32 v75, v75
	v_add_f32_e32 v200, v200, v74
	v_fma_f32 v76, v76, s84, -v199
	s_waitcnt lgkmcnt(5)
	v_mfma_f32_32x32x16_bf16 v[80:95], v[206:209], v[124:127], v[80:95]
	ds_read_b128 v[168:171], v173 offset:4608
	v_exp_f32_e32 v76, v76
	v_add_f32_e32 v200, v200, v75
	v_fma_f32 v77, v77, s84, -v199
	v_exp_f32_e32 v77, v77
	s_waitcnt lgkmcnt(5)
	v_mfma_f32_32x32x16_bf16 v[80:95], v[210:213], v[160:163], v[80:95]
	ds_read_b128 v[176:179], v173 offset:9216
	v_add_f32_e32 v200, v200, v76
	v_fma_f32 v78, v78, s84, -v199
	v_exp_f32_e32 v78, v78
	v_add_f32_e32 v200, v200, v77
	s_waitcnt lgkmcnt(5)
	v_mfma_f32_32x32x16_bf16 v[80:95], v[214:217], v[152:155], v[80:95]
	ds_read_b128 v[226:229], v173 offset:13824
	v_fma_f32 v79, v79, s84, -v199
	v_exp_f32_e32 v79, v79
	v_add_f32_e32 v200, v200, v78
	v_add_f32_e32 v200, v200, v79
	s_waitcnt lgkmcnt(5)
	v_mfma_f32_32x32x16_bf16 v[80:95], v[218:221], v[156:159], v[80:95]
	v_cvt_pk_bf16_f32 v64, v64, v65
	v_cvt_pk_bf16_f32 v65, v66, v67
	v_cvt_pk_bf16_f32 v66, v68, v69
	v_cvt_pk_bf16_f32 v67, v70, v71
	s_waitcnt lgkmcnt(4)
	v_mfma_f32_32x32x16_bf16 v[80:95], v[222:225], v[148:151], v[80:95]
	v_cvt_pk_bf16_f32 v68, v72, v73
	v_cvt_pk_bf16_f32 v69, v74, v75
	v_cvt_pk_bf16_f32 v70, v76, v77
	v_cvt_pk_bf16_f32 v71, v78, v79
	s_waitcnt lgkmcnt(3)
	v_mfma_f32_32x32x16_bf16 v[48:63], v[164:167], v[64:67], v[48:63]
	ds_read_b128 v[164:167], v173 offset:32
	s_waitcnt lgkmcnt(3)
	v_mfma_f32_32x32x16_bf16 v[32:47], v[168:171], v[64:67], v[32:47]
	ds_read_b128 v[168:171], v173 offset:4640
	s_waitcnt lgkmcnt(3)
	v_mfma_f32_32x32x16_bf16 v[16:31], v[176:179], v[64:67], v[16:31]
	ds_read_b128 v[176:179], v173 offset:9248
	s_waitcnt lgkmcnt(3)
	v_mfma_f32_32x32x16_bf16 v[0:15], v[226:229], v[64:67], v[0:15]
	ds_read_b128 v[226:229], v173 offset:13856
	ds_read_b128 v[202:205], v174 offset:12800
	ds_read_b128 v[206:209], v174 offset:12832
	ds_read_b128 v[210:213], v174 offset:12864
	ds_read_b128 v[214:217], v174 offset:12896
	ds_read_b128 v[218:221], v174 offset:12928
	ds_read_b128 v[222:225], v174 offset:12960
	s_cmp_gt_i32 s33, s97
	s_cbranch_scc1 .Lat_mask_a
.Lat_mask_a_ret:
	s_waitcnt lgkmcnt(9)
	v_mfma_f32_32x32x16_bf16 v[48:63], v[164:167], v[68:71], v[48:63]
	v_add_f32_e32 v175, 0x41000000, v199
	v_max3_f32 v172, v80, v81, v82
	v_max3_f32 v172, v172, v83, v84
	s_waitcnt lgkmcnt(8)
	v_mfma_f32_32x32x16_bf16 v[32:47], v[168:171], v[68:71], v[32:47]
	v_max3_f32 v172, v172, v85, v86
	v_max3_f32 v172, v172, v87, v88
	v_max3_f32 v172, v172, v89, v90
	s_waitcnt lgkmcnt(7)
	v_mfma_f32_32x32x16_bf16 v[16:31], v[176:179], v[68:71], v[16:31]
	v_max3_f32 v172, v172, v91, v92
	v_max3_f32 v172, v172, v93, v94
	v_max_f32_e32 v172, v172, v95
	s_waitcnt lgkmcnt(6)
	v_mfma_f32_32x32x16_bf16 v[0:15], v[226:229], v[68:71], v[0:15]
	v_mul_f32_e32 v172, 0x3dd53b94, v172
	v_cmp_gt_f32_e32 vcc, v172, v175
	s_cmp_lg_u64 vcc, 0
	s_cbranch_scc1 .Lat_resc_a
.Lat_resc_a_ret:
	v_fma_f32 v80, v80, s84, -v199
	v_exp_f32_e32 v80, v80
	v_fma_f32 v81, v81, s84, -v199
	v_exp_f32_e32 v81, v81
	v_add_f32_e32 v200, v200, v80
	v_fma_f32 v82, v82, s84, -v199
	v_exp_f32_e32 v82, v82
	v_add_f32_e32 v200, v200, v81
	s_waitcnt lgkmcnt(5)
	v_mfma_f32_32x32x16_bf16 v[64:79], v[202:205], v[96:99], 0
	ds_read_b128 v[202:205], v174 offset:12992
	v_fma_f32 v83, v83, s84, -v199
	v_exp_f32_e32 v83, v83
	v_add_f32_e32 v200, v200, v82
	v_fma_f32 v84, v84, s84, -v199
	s_waitcnt lgkmcnt(5)
	v_mfma_f32_32x32x16_bf16 v[64:79], v[206:209], v[100:103], v[64:79]
	ds_read_b128 v[206:209], v174 offset:13024
	v_exp_f32_e32 v84, v84
	v_add_f32_e32 v200, v200, v83
	v_fma_f32 v85, v85, s84, -v199
	v_exp_f32_e32 v85, v85
	s_waitcnt lgkmcnt(5)
	v_mfma_f32_32x32x16_bf16 v[64:79], v[210:213], v[104:107], v[64:79]
	ds_read_b128 v[210:213], v174 offset:13056
	v_add_f32_e32 v200, v200, v84
	v_fma_f32 v86, v86, s84, -v199
	v_exp_f32_e32 v86, v86
	v_add_f32_e32 v200, v200, v85
	s_waitcnt lgkmcnt(5)
	v_mfma_f32_32x32x16_bf16 v[64:79], v[214:217], v[108:111], v[64:79]
	ds_read_b128 v[214:217], v174 offset:13088
	v_fma_f32 v87, v87, s84, -v199
	v_exp_f32_e32 v87, v87
	v_add_f32_e32 v200, v200, v86
	v_fma_f32 v88, v88, s84, -v199
	s_waitcnt lgkmcnt(5)
	v_mfma_f32_32x32x16_bf16 v[64:79], v[218:221], v[112:115], v[64:79]
	ds_read_b128 v[218:221], v174 offset:13120
	v_exp_f32_e32 v88, v88
	v_add_f32_e32 v200, v200, v87
	v_fma_f32 v89, v89, s84, -v199
	v_exp_f32_e32 v89, v89
	s_waitcnt lgkmcnt(5)
	v_mfma_f32_32x32x16_bf16 v[64:79], v[222:225], v[116:119], v[64:79]
	ds_read_b128 v[222:225], v174 offset:13152
	v_add_f32_e32 v200, v200, v88
	v_fma_f32 v90, v90, s84, -v199
	v_exp_f32_e32 v90, v90
	v_add_f32_e32 v200, v200, v89
	s_waitcnt lgkmcnt(5)
	v_mfma_f32_32x32x16_bf16 v[64:79], v[202:205], v[120:123], v[64:79]
	ds_read_b128 v[164:167], v234 offset:51200
	v_fma_f32 v91, v91, s84, -v199
	v_exp_f32_e32 v91, v91
	v_add_f32_e32 v200, v200, v90
	v_fma_f32 v92, v92, s84, -v199
	s_waitcnt lgkmcnt(5)
	v_mfma_f32_32x32x16_bf16 v[64:79], v[206:209], v[124:127], v[64:79]
	ds_read_b128 v[168:171], v234 offset:55808
	v_exp_f32_e32 v92, v92
	v_add_f32_e32 v200, v200, v91
	v_fma_f32 v93, v93, s84, -v199
	v_exp_f32_e32 v93, v93
	s_waitcnt lgkmcnt(5)
	v_mfma_f32_32x32x16_bf16 v[64:79], v[210:213], v[160:163], v[64:79]
	ds_read_b128 v[176:179], v234 offset:60416
	v_add_f32_e32 v200, v200, v92
	v_fma_f32 v94, v94, s84, -v199
	v_exp_f32_e32 v94, v94
	v_add_f32_e32 v200, v200, v93
	s_waitcnt lgkmcnt(5)
	v_mfma_f32_32x32x16_bf16 v[64:79], v[214:217], v[152:155], v[64:79]
	ds_read_b128 v[226:229], v234 offset:65024
	v_fma_f32 v95, v95, s84, -v199
	v_exp_f32_e32 v95, v95
	v_add_f32_e32 v200, v200, v94
	v_add_f32_e32 v200, v200, v95
	s_waitcnt lgkmcnt(5)
	v_mfma_f32_32x32x16_bf16 v[64:79], v[218:221], v[156:159], v[64:79]
	v_cvt_pk_bf16_f32 v80, v80, v81
	v_cvt_pk_bf16_f32 v81, v82, v83
	v_cvt_pk_bf16_f32 v82, v84, v85
	v_cvt_pk_bf16_f32 v83, v86, v87
	s_waitcnt lgkmcnt(4)
	v_mfma_f32_32x32x16_bf16 v[64:79], v[222:225], v[148:151], v[64:79]
	v_cvt_pk_bf16_f32 v84, v88, v89
	v_cvt_pk_bf16_f32 v85, v90, v91
	v_cvt_pk_bf16_f32 v86, v92, v93
	v_cvt_pk_bf16_f32 v87, v94, v95
	s_waitcnt lgkmcnt(3)
	v_mfma_f32_32x32x16_bf16 v[48:63], v[164:167], v[80:83], v[48:63]
	ds_read_b128 v[164:167], v234 offset:51232
	s_waitcnt lgkmcnt(3)
	v_mfma_f32_32x32x16_bf16 v[32:47], v[168:171], v[80:83], v[32:47]
	ds_read_b128 v[168:171], v234 offset:55840
	s_waitcnt lgkmcnt(3)
	v_mfma_f32_32x32x16_bf16 v[16:31], v[176:179], v[80:83], v[16:31]
	ds_read_b128 v[176:179], v234 offset:60448
	s_waitcnt lgkmcnt(3)
	v_mfma_f32_32x32x16_bf16 v[0:15], v[226:229], v[80:83], v[0:15]
	ds_read_b128 v[226:229], v234 offset:65056
	s_cmp_gt_i32 s33, s97
	s_cbranch_scc1 .Lat_mask_b
.Lat_mask_b_ret:
	s_waitcnt lgkmcnt(3)
	v_mfma_f32_32x32x16_bf16 v[48:63], v[164:167], v[84:87], v[48:63]
	v_add_f32_e32 v175, 0x41000000, v199
	v_max3_f32 v172, v64, v65, v66
	v_max3_f32 v172, v172, v67, v68
	s_waitcnt lgkmcnt(2)
	v_mfma_f32_32x32x16_bf16 v[32:47], v[168:171], v[84:87], v[32:47]
	v_max3_f32 v172, v172, v69, v70
	v_max3_f32 v172, v172, v71, v72
	v_max3_f32 v172, v172, v73, v74
	s_waitcnt lgkmcnt(1)
	v_mfma_f32_32x32x16_bf16 v[16:31], v[176:179], v[84:87], v[16:31]
	v_max3_f32 v172, v172, v75, v76
	v_max3_f32 v172, v172, v77, v78
	v_max_f32_e32 v172, v172, v79
	s_waitcnt lgkmcnt(0)
	v_mfma_f32_32x32x16_bf16 v[0:15], v[226:229], v[84:87], v[0:15]
	v_mul_f32_e32 v172, 0x3dd53b94, v172
	v_cmp_gt_f32_e32 vcc, v172, v175
	s_cmp_lg_u64 vcc, 0
	s_cbranch_scc1 .Lat_resc_b
.Lat_resc_b_ret:
	s_cmp_lt_i32 s54, s53
	s_cbranch_scc0 .Lat_skip_st
	s_waitcnt vmcnt(0)
	s_bitcmp1_b32 s54, 0
	s_cselect_b32 s4, 0x6400, 0
	v_add_u32_e32 v235, s4, v194
	ds_write_b128 v235, v[128:131]
	ds_write_b128 v235, v[132:135] offset:12800
	v_add_u32_e32 v235, s4, v184
	ds_write_b128 v235, v[136:139] offset:256
	s_add_i32 s4, s52, 1
	s_cmp_lg_u32 s52, 2
	s_cselect_b32 s4, s4, 0
	s_mul_i32 s4, s4, 0x4800
	v_add_u32_e32 v235, s4, v185
	v_add_u32_e32 v245, 0xc800, v235
	v_add_u32_e32 v235, 0xe800, v235
	ds_write2_b64 v245, v[140:141], v[142:143] offset1:2
	ds_write2_b64 v235, v[144:145], v[146:147] offset0:128 offset1:130
.Lat_skip_st:
	s_add_i32 s4, s54, 1
	s_cmp_lt_i32 s4, s53
	s_cbranch_scc0 .Lat_skip_ld
	v_add_u32_e32 v186, 0x10000, v186
	v_add_u32_e32 v188, 0x1000, v188
	v_add_u32_e32 v180, 0xffff8000, v186
	v_lshl_add_u64 v[244:245], v[180:181], 1, s[64:65]
	global_load_dwordx4 v[128:131], v[244:245], off
	v_lshl_add_u64 v[244:245], v[186:187], 1, s[64:65]
	global_load_dwordx4 v[132:135], v[244:245], off
	v_lshl_add_u64 v[244:245], v[188:189], 1, s[60:61]
	global_load_dwordx4 v[136:139], v[244:245], off
	v_add_u32_e32 v235, s33, v198
	v_add_u32_e32 v180, 65, v235
	v_lshl_add_u64 v[244:245], v[180:181], 1, s[68:69]
	global_load_dwordx4 v[140:143], v[244:245], off
	v_add_u32_e32 v180, 0x200041, v235
	v_lshl_add_u64 v[244:245], v[180:181], 1, s[68:69]
	global_load_dwordx4 v[144:147], v[244:245], off
.Lat_skip_ld:
	s_add_i32 s4, s52, 1
	s_cmp_lg_u32 s52, 2
	s_cselect_b32 s52, s4, 0
	s_add_i32 s33, s33, 64
	v_subrev_u32_e32 v197, 64, v197
	v_add_u32_e32 v173, 0xc840, v234
	s_mov_b32 s0, s54
	s_cmp_eq_u32 s53, s54
	s_waitcnt lgkmcnt(0)
	s_barrier
	s_cbranch_scc0 .LBB0_1340
	v_fma_f32 v64, v64, s84, -v199
	v_exp_f32_e32 v64, v64
	v_fma_f32 v65, v65, s84, -v199
	v_exp_f32_e32 v65, v65
	v_add_f32_e32 v200, v200, v64
	v_fma_f32 v66, v66, s84, -v199
	v_exp_f32_e32 v66, v66
	v_add_f32_e32 v200, v200, v65
	v_fma_f32 v67, v67, s84, -v199
	v_exp_f32_e32 v67, v67
	v_add_f32_e32 v200, v200, v66
	v_fma_f32 v68, v68, s84, -v199
	v_exp_f32_e32 v68, v68
	v_add_f32_e32 v200, v200, v67
	v_fma_f32 v69, v69, s84, -v199
	v_exp_f32_e32 v69, v69
	v_add_f32_e32 v200, v200, v68
	v_fma_f32 v70, v70, s84, -v199
	v_exp_f32_e32 v70, v70
	v_add_f32_e32 v200, v200, v69
	v_fma_f32 v71, v71, s84, -v199
	v_exp_f32_e32 v71, v71
	v_add_f32_e32 v200, v200, v70
	v_fma_f32 v72, v72, s84, -v199
	v_exp_f32_e32 v72, v72
	v_add_f32_e32 v200, v200, v71
	v_fma_f32 v73, v73, s84, -v199
	v_exp_f32_e32 v73, v73
	v_add_f32_e32 v200, v200, v72
	v_fma_f32 v74, v74, s84, -v199
	v_exp_f32_e32 v74, v74
	v_add_f32_e32 v200, v200, v73
	v_fma_f32 v75, v75, s84, -v199
	v_exp_f32_e32 v75, v75
	v_add_f32_e32 v200, v200, v74
	v_fma_f32 v76, v76, s84, -v199
	v_exp_f32_e32 v76, v76
	v_add_f32_e32 v200, v200, v75
	v_fma_f32 v77, v77, s84, -v199
	v_exp_f32_e32 v77, v77
	v_add_f32_e32 v200, v200, v76
	v_fma_f32 v78, v78, s84, -v199
	v_exp_f32_e32 v78, v78
	v_add_f32_e32 v200, v200, v77
	v_fma_f32 v79, v79, s84, -v199
	v_exp_f32_e32 v79, v79
	v_add_f32_e32 v200, v200, v78
	v_add_f32_e32 v200, v200, v79
	v_cvt_pk_bf16_f32 v236, v64, v65
	v_cvt_pk_bf16_f32 v237, v66, v67
	v_cvt_pk_bf16_f32 v238, v68, v69
	v_cvt_pk_bf16_f32 v239, v70, v71
	v_cvt_pk_bf16_f32 v240, v72, v73
	v_cvt_pk_bf16_f32 v241, v74, v75
	v_cvt_pk_bf16_f32 v242, v76, v77
	v_cvt_pk_bf16_f32 v243, v78, v79
	v_mov_b32_e32 v68, v236
	v_mov_b32_e32 v69, v237
	v_mov_b32_e32 v70, v238
	v_mov_b32_e32 v71, v239
	v_mov_b32_e32 v64, v240
	v_mov_b32_e32 v65, v241
	v_mov_b32_e32 v66, v242
	v_mov_b32_e32 v67, v243
	s_branch .LBB0_1332
.Lat_mask_a:
	s_nop 7
	v_cmp_gt_i32_e64 s[4:5], 0, v197
	v_cmp_gt_i32_e64 s[6:7], 1, v197
	v_cmp_gt_i32_e64 s[8:9], 2, v197
	v_cmp_gt_i32_e64 s[10:11], 3, v197
	v_cmp_gt_i32_e64 s[12:13], 8, v197
	v_cmp_gt_i32_e64 s[14:15], 9, v197
	v_cmp_gt_i32_e64 s[16:17], 10, v197
	v_cmp_gt_i32_e64 s[18:19], 11, v197
	v_cndmask_b32_e64 v80, v80, v192, s[4:5]
	v_cndmask_b32_e64 v81, v81, v192, s[6:7]
	v_cndmask_b32_e64 v82, v82, v192, s[8:9]
	v_cndmask_b32_e64 v83, v83, v192, s[10:11]
	v_cndmask_b32_e64 v84, v84, v192, s[12:13]
	v_cndmask_b32_e64 v85, v85, v192, s[14:15]
	v_cndmask_b32_e64 v86, v86, v192, s[16:17]
	v_cndmask_b32_e64 v87, v87, v192, s[18:19]
	v_cmp_gt_i32_e64 s[4:5], 16, v197
	v_cmp_gt_i32_e64 s[6:7], 17, v197
	v_cmp_gt_i32_e64 s[8:9], 18, v197
	v_cmp_gt_i32_e64 s[10:11], 19, v197
	v_cmp_gt_i32_e64 s[12:13], 24, v197
	v_cmp_gt_i32_e64 s[14:15], 25, v197
	v_cmp_gt_i32_e64 s[16:17], 26, v197
	v_cmp_gt_i32_e64 s[18:19], 27, v197
	v_cndmask_b32_e64 v88, v88, v192, s[4:5]
	v_cndmask_b32_e64 v89, v89, v192, s[6:7]
	v_cndmask_b32_e64 v90, v90, v192, s[8:9]
	v_cndmask_b32_e64 v91, v91, v192, s[10:11]
	v_cndmask_b32_e64 v92, v92, v192, s[12:13]
	v_cndmask_b32_e64 v93, v93, v192, s[14:15]
	v_cndmask_b32_e64 v94, v94, v192, s[16:17]
	v_cndmask_b32_e64 v95, v95, v192, s[18:19]
	s_branch .Lat_mask_a_ret
.Lat_mask_b:
	s_nop 7
	v_cmp_gt_i32_e64 s[4:5], 32, v197
	v_cmp_gt_i32_e64 s[6:7], 33, v197
	v_cmp_gt_i32_e64 s[8:9], 34, v197
	v_cmp_gt_i32_e64 s[10:11], 35, v197
	v_cmp_gt_i32_e64 s[12:13], 40, v197
	v_cmp_gt_i32_e64 s[14:15], 41, v197
	v_cmp_gt_i32_e64 s[16:17], 42, v197
	v_cmp_gt_i32_e64 s[18:19], 43, v197
	v_cndmask_b32_e64 v64, v64, v192, s[4:5]
	v_cndmask_b32_e64 v65, v65, v192, s[6:7]
	v_cndmask_b32_e64 v66, v66, v192, s[8:9]
	v_cndmask_b32_e64 v67, v67, v192, s[10:11]
	v_cndmask_b32_e64 v68, v68, v192, s[12:13]
	v_cndmask_b32_e64 v69, v69, v192, s[14:15]
	v_cndmask_b32_e64 v70, v70, v192, s[16:17]
	v_cndmask_b32_e64 v71, v71, v192, s[18:19]
	v_cmp_gt_i32_e64 s[4:5], 48, v197
	v_cmp_gt_i32_e64 s[6:7], 49, v197
	v_cmp_gt_i32_e64 s[8:9], 50, v197
	v_cmp_gt_i32_e64 s[10:11], 51, v197
	v_cmp_gt_i32_e64 s[12:13], 56, v197
	v_cmp_gt_i32_e64 s[14:15], 57, v197
	v_cmp_gt_i32_e64 s[16:17], 58, v197
	v_cmp_gt_i32_e64 s[18:19], 59, v197
	v_cndmask_b32_e64 v72, v72, v192, s[4:5]
	v_cndmask_b32_e64 v73, v73, v192, s[6:7]
	v_cndmask_b32_e64 v74, v74, v192, s[8:9]
	v_cndmask_b32_e64 v75, v75, v192, s[10:11]
	v_cndmask_b32_e64 v76, v76, v192, s[12:13]
	v_cndmask_b32_e64 v77, v77, v192, s[14:15]
	v_cndmask_b32_e64 v78, v78, v192, s[16:17]
	v_cndmask_b32_e64 v79, v79, v192, s[18:19]
	s_branch .Lat_mask_b_ret
.Lat_resc_a:
	ds_bpermute_b32 v175, v246, v172
	s_waitcnt lgkmcnt(0)
	v_max3_f32 v175, v199, v172, v175
	v_sub_f32_e32 v172, v199, v175
	v_exp_f32_e32 v172, v172
	v_mov_b32_e32 v199, v175
	s_nop 0
	v_mul_f32_e32 v200, v200, v172
	s_nop 15
	s_nop 3
	v_mul_f32_e32 v0, v172, v0
	v_mul_f32_e32 v1, v172, v1
	v_mul_f32_e32 v2, v172, v2
	v_mul_f32_e32 v3, v172, v3
	v_mul_f32_e32 v4, v172, v4
	v_mul_f32_e32 v5, v172, v5
	v_mul_f32_e32 v6, v172, v6
	v_mul_f32_e32 v7, v172, v7
	v_mul_f32_e32 v8, v172, v8
	v_mul_f32_e32 v9, v172, v9
	v_mul_f32_e32 v10, v172, v10
	v_mul_f32_e32 v11, v172, v11
	v_mul_f32_e32 v12, v172, v12
	v_mul_f32_e32 v13, v172, v13
	v_mul_f32_e32 v14, v172, v14
	v_mul_f32_e32 v15, v172, v15
	v_mul_f32_e32 v16, v172, v16
	v_mul_f32_e32 v17, v172, v17
	v_mul_f32_e32 v18, v172, v18
	v_mul_f32_e32 v19, v172, v19
	v_mul_f32_e32 v20, v172, v20
	v_mul_f32_e32 v21, v172, v21
	v_mul_f32_e32 v22, v172, v22
	v_mul_f32_e32 v23, v172, v23
	v_mul_f32_e32 v24, v172, v24
	v_mul_f32_e32 v25, v172, v25
	v_mul_f32_e32 v26, v172, v26
	v_mul_f32_e32 v27, v172, v27
	v_mul_f32_e32 v28, v172, v28
	v_mul_f32_e32 v29, v172, v29
	v_mul_f32_e32 v30, v172, v30
	v_mul_f32_e32 v31, v172, v31
	v_mul_f32_e32 v32, v172, v32
	v_mul_f32_e32 v33, v172, v33
	v_mul_f32_e32 v34, v172, v34
	v_mul_f32_e32 v35, v172, v35
	v_mul_f32_e32 v36, v172, v36
	v_mul_f32_e32 v37, v172, v37
	v_mul_f32_e32 v38, v172, v38
	v_mul_f32_e32 v39, v172, v39
	v_mul_f32_e32 v40, v172, v40
	v_mul_f32_e32 v41, v172, v41
	v_mul_f32_e32 v42, v172, v42
	v_mul_f32_e32 v43, v172, v43
	v_mul_f32_e32 v44, v172, v44
	v_mul_f32_e32 v45, v172, v45
	v_mul_f32_e32 v46, v172, v46
	v_mul_f32_e32 v47, v172, v47
	v_mul_f32_e32 v48, v172, v48
	v_mul_f32_e32 v49, v172, v49
	v_mul_f32_e32 v50, v172, v50
	v_mul_f32_e32 v51, v172, v51
	v_mul_f32_e32 v52, v172, v52
	v_mul_f32_e32 v53, v172, v53
	v_mul_f32_e32 v54, v172, v54
	v_mul_f32_e32 v55, v172, v55
	v_mul_f32_e32 v56, v172, v56
	v_mul_f32_e32 v57, v172, v57
	v_mul_f32_e32 v58, v172, v58
	v_mul_f32_e32 v59, v172, v59
	v_mul_f32_e32 v60, v172, v60
	v_mul_f32_e32 v61, v172, v61
	v_mul_f32_e32 v62, v172, v62
	v_mul_f32_e32 v63, v172, v63
	s_branch .Lat_resc_a_ret
